# stack + non-temporal loads for the read-once partial streams in the combine phase
# speedup vs baseline: 1.0093x; 1.0093x over previous
.LBB0_465:
	v_lshl_add_u64 v[6:7], s[20:21], 0, v[4:5]
	v_add_co_u32_e32 v8, vcc, 0x1f100000, v6
	v_mov_b32_e32 v16, 0
	s_nop 0
	v_addc_co_u32_e32 v9, vcc, 0, v7, vcc
	v_add_co_u32_e32 v10, vcc, 0x1f300000, v6
	v_mov_b32_e32 v17, v16
	s_nop 0
	v_addc_co_u32_e32 v11, vcc, 0, v7, vcc
	v_add_co_u32_e32 v12, vcc, 0x1f500000, v6
	v_mov_b64_e32 v[18:19], v[16:17]
	s_nop 0
	v_addc_co_u32_e32 v13, vcc, 0, v7, vcc
	v_add_co_u32_e32 v6, vcc, 0x1f700000, v6
	v_mov_b64_e32 v[20:21], v[16:17]
	s_nop 0
	v_addc_co_u32_e32 v7, vcc, 0, v7, vcc
	global_load_dword v14, v[8:9], off
	global_load_dword v27, v[10:11], off
	global_load_dword v26, v[12:13], off
	global_load_dword v24, v[6:7], off
	v_lshl_add_u64 v[62:63], s[20:21], 0, v[2:3]
	v_add_co_u32_e32 v46, vcc, 0x13100000, v62
	s_nop 1
	v_addc_co_u32_e32 v47, vcc, 0, v63, vcc
	global_load_dwordx4 v[46:49], v[46:47], off nt
	v_add_co_u32_e32 v50, vcc, 0x15100000, v62
	s_nop 1
	v_addc_co_u32_e32 v51, vcc, 0, v63, vcc
	global_load_dwordx4 v[50:53], v[50:51], off nt
	v_add_co_u32_e32 v54, vcc, 0x17100000, v62
	s_nop 1
	v_addc_co_u32_e32 v55, vcc, 0, v63, vcc
	global_load_dwordx4 v[54:57], v[54:55], off nt
	v_lshl_add_u64 v[58:59], s[18:19], 0, v[2:3]
	global_load_dwordx4 v[58:61], v[58:59], off nt
	v_mov_b64_e32 v[6:7], v[16:17]
	v_mov_b64_e32 v[8:9], v[16:17]
	v_mov_b64_e32 v[10:11], v[16:17]
	v_mov_b64_e32 v[12:13], v[16:17]
	v_mov_b64_e32 v[22:23], v[16:17]
	s_waitcnt vmcnt(6)
	v_max3_f32 v15, v14, s10, v27
	s_waitcnt vmcnt(4)
	v_max3_f32 v25, v15, v26, v24
	v_sub_f32_e32 v14, v14, v25
	v_exp_f32_e32 v28, v14
	v_mov_b64_e32 v[14:15], v[16:17]
	v_cmp_lt_f32_e32 vcc, 0, v28
	s_and_saveexec_b64 s[8:9], vcc
	s_cbranch_execz .LBB0_467
	v_mul_f32_e32 v16, 0x3d800000, v28
	s_waitcnt vmcnt(3)
	v_cvt_pk_f32_fp8_e32 v[10:11], v46
	v_cvt_pk_f32_fp8_sdwa v[12:13], v46 src0_sel:WORD_1
	v_cvt_pk_f32_fp8_e32 v[14:15], v47
	v_cvt_pk_f32_fp8_sdwa v[6:7], v47 src0_sel:WORD_1
	v_cvt_pk_f32_fp8_e32 v[30:31], v48
	v_cvt_pk_f32_fp8_sdwa v[32:33], v48 src0_sel:WORD_1
	v_cvt_pk_f32_fp8_e32 v[34:35], v49
	v_cvt_pk_f32_fp8_sdwa v[36:37], v49 src0_sel:WORD_1
	v_pk_fma_f32 v[22:23], v[16:17], v[10:11], 0 op_sel_hi:[0,1,0]
	v_pk_fma_f32 v[20:21], v[16:17], v[12:13], 0 op_sel_hi:[0,1,0]
	v_pk_fma_f32 v[18:19], v[16:17], v[14:15], 0 op_sel_hi:[0,1,0]
	v_pk_fma_f32 v[14:15], v[16:17], v[6:7], 0 op_sel_hi:[0,1,0]
	v_pk_fma_f32 v[12:13], v[16:17], v[30:31], 0 op_sel_hi:[0,1,0]
	v_pk_fma_f32 v[10:11], v[16:17], v[32:33], 0 op_sel_hi:[0,1,0]
	v_pk_fma_f32 v[8:9], v[16:17], v[34:35], 0 op_sel_hi:[0,1,0]
	v_pk_fma_f32 v[6:7], v[16:17], v[36:37], 0 op_sel_hi:[0,1,0]
	v_mov_b32_e32 v16, v28
